# v093 with the P10 token barrier moved behind the issue of the token's h/index/gate loads (barrier wait overlaps their latency)
# speedup vs baseline: 1.0077x; 1.0077x over previous
; __device__ __forceinline__ float bf_lo(unsigned u) { return __uint_as_float(u << 16); }
; __device__ __forceinline__ float bf_hi(unsigned u) { return __uint_as_float(u & 0xffff0000u); }
; __global__ void __launch_bounds__(NT, 2) mk_fwd(Args args) {
;     ...
;         for (int tok = gw; tok < MTOK; tok += NGW) {
;             const int b = tok >> 11;
;             f32x2 hf2[16];
; #pragma unroll
;             for (int j = 0; j < 4; ++j) { const u32x4 a = *(const u32x4*)(HB + (size_t)tok * DM + lane * 32 + j * 8);
; #pragma unroll
;                 for (int q = 0; q < 4; ++q) hf2[j * 4 + q] = (f32x2){bf_lo(a[q]), bf_hi(a[q])}; }
;             const int e0 = EIDX[(size_t)tok * 128 + lane], e1 = EIDX[(size_t)tok * 128 + 64 + lane];
;             const float g0 = GATE[(size_t)tok * 128 + lane], g1 = GATE[(size_t)tok * 128 + 64 + lane];
;             const bool hi32 = (lane & 32) != 0, hi16 = (lane & 16) != 0; const int l3 = (lane & 3) << 4;
.LBB0_886:
	s_ashr_i32 s71, s70, 31
	s_lshl_b64 s[4:5], s[70:71], 9
	v_lshl_or_b32 v0, v128, 2, s4
	v_mov_b32_e32 v1, s5
	v_lshl_add_u64 v[2:3], s[46:47], 0, v[0:1]
	global_load_dword v108, v[2:3], off
	s_lshl_b64 s[4:5], s[70:71], 12
	v_lshl_add_u64 v[2:3], v[96:97], 0, s[4:5]
	global_load_dwordx4 v[32:35], v[2:3], off offset:48
	global_load_dwordx4 v[36:39], v[2:3], off offset:32
	global_load_dwordx4 v[40:43], v[2:3], off offset:16
	global_load_dwordx4 v[44:47], v[2:3], off
	v_or_b32_e32 v2, 0x100, v0
	v_mov_b32_e32 v3, v1
	v_lshl_add_u64 v[0:1], s[48:49], 0, v[0:1]
	v_lshl_add_u64 v[4:5], s[46:47], 0, v[2:3]
	v_lshl_add_u64 v[2:3], s[48:49], 0, v[2:3]
	global_load_dword v106, v[4:5], off
	global_load_dword v110, v[0:1], off
	global_load_dword v156, v[2:3], off
	s_cmp_eq_u32 s84, 0x100
	s_cbranch_scc0 .Lp10_nobar
	s_barrier
.Lp10_nobar:
	s_waitcnt vmcnt(0)
	v_lshl_or_b32 v170, v108, 7, v128
	v_lshlrev_b32_e32 v171, 7, v106
	v_or_b32_e32 v174, 64, v128
	v_or_b32_e32 v171, v171, v174
	s_nop 0
	s_xnor_b64 s[62:63], s[50:51], s[52:53]
	s_nop 1
	v_min_u32_dpp v172, v170, v170 quad_perm:[1,0,3,2] row_mask:0xf bank_mask:0xf
	v_max_u32_dpp v173, v170, v170 quad_perm:[1,0,3,2] row_mask:0xf bank_mask:0xf
	v_min_u32_dpp v175, v171, v171 quad_perm:[1,0,3,2] row_mask:0xf bank_mask:0xf
	v_max_u32_dpp v176, v171, v171 quad_perm:[1,0,3,2] row_mask:0xf bank_mask:0xf
	v_cndmask_b32_e64 v170, v173, v172, s[62:63]
	v_cndmask_b32_e64 v171, v176, v175, s[62:63]
	s_xnor_b64 s[62:63], s[52:53], s[54:55]
	s_nop 1
	v_min_u32_dpp v172, v170, v170 quad_perm:[2,3,0,1] row_mask:0xf bank_mask:0xf
	v_max_u32_dpp v173, v170, v170 quad_perm:[2,3,0,1] row_mask:0xf bank_mask:0xf
	v_min_u32_dpp v175, v171, v171 quad_perm:[2,3,0,1] row_mask:0xf bank_mask:0xf
	v_max_u32_dpp v176, v171, v171 quad_perm:[2,3,0,1] row_mask:0xf bank_mask:0xf
	v_cndmask_b32_e64 v170, v173, v172, s[62:63]
	v_cndmask_b32_e64 v171, v176, v175, s[62:63]
	s_xnor_b64 s[62:63], s[50:51], s[54:55]
	s_nop 1
	v_min_u32_dpp v172, v170, v170 quad_perm:[1,0,3,2] row_mask:0xf bank_mask:0xf
	v_max_u32_dpp v173, v170, v170 quad_perm:[1,0,3,2] row_mask:0xf bank_mask:0xf
	v_min_u32_dpp v175, v171, v171 quad_perm:[1,0,3,2] row_mask:0xf bank_mask:0xf
	v_max_u32_dpp v176, v171, v171 quad_perm:[1,0,3,2] row_mask:0xf bank_mask:0xf
	v_cndmask_b32_e64 v170, v173, v172, s[62:63]
	v_cndmask_b32_e64 v171, v176, v175, s[62:63]
	s_xnor_b64 s[62:63], s[54:55], s[56:57]
	s_nop 1
	v_mov_b32_dpp v174, v170 row_half_mirror row_mask:0xf bank_mask:0xf
	v_mov_b32_dpp v177, v171 row_half_mirror row_mask:0xf bank_mask:0xf
	s_nop 0
	v_min_u32_dpp v172, v174, v170 quad_perm:[3,2,1,0] row_mask:0xf bank_mask:0xf
	v_max_u32_dpp v173, v174, v170 quad_perm:[3,2,1,0] row_mask:0xf bank_mask:0xf
	v_min_u32_dpp v175, v177, v171 quad_perm:[3,2,1,0] row_mask:0xf bank_mask:0xf
	v_max_u32_dpp v176, v177, v171 quad_perm:[3,2,1,0] row_mask:0xf bank_mask:0xf
	v_cndmask_b32_e64 v170, v173, v172, s[62:63]
	v_cndmask_b32_e64 v171, v176, v175, s[62:63]
	s_xnor_b64 s[62:63], s[52:53], s[56:57]
	s_nop 1
	v_min_u32_dpp v172, v170, v170 quad_perm:[2,3,0,1] row_mask:0xf bank_mask:0xf
	v_max_u32_dpp v173, v170, v170 quad_perm:[2,3,0,1] row_mask:0xf bank_mask:0xf
	v_min_u32_dpp v175, v171, v171 quad_perm:[2,3,0,1] row_mask:0xf bank_mask:0xf
	v_max_u32_dpp v176, v171, v171 quad_perm:[2,3,0,1] row_mask:0xf bank_mask:0xf
	v_cndmask_b32_e64 v170, v173, v172, s[62:63]
	v_cndmask_b32_e64 v171, v176, v175, s[62:63]
	s_xnor_b64 s[62:63], s[50:51], s[56:57]
	s_nop 1
	v_min_u32_dpp v172, v170, v170 quad_perm:[1,0,3,2] row_mask:0xf bank_mask:0xf
	v_max_u32_dpp v173, v170, v170 quad_perm:[1,0,3,2] row_mask:0xf bank_mask:0xf
	v_min_u32_dpp v175, v171, v171 quad_perm:[1,0,3,2] row_mask:0xf bank_mask:0xf
	v_max_u32_dpp v176, v171, v171 quad_perm:[1,0,3,2] row_mask:0xf bank_mask:0xf
	v_cndmask_b32_e64 v170, v173, v172, s[62:63]
	v_cndmask_b32_e64 v171, v176, v175, s[62:63]
	s_xnor_b64 s[62:63], s[56:57], s[58:59]
	s_nop 1
	v_min_u32_dpp v172, v170, v170 row_ror:8 row_mask:0xf bank_mask:0xf
	v_max_u32_dpp v173, v170, v170 row_ror:8 row_mask:0xf bank_mask:0xf
	v_min_u32_dpp v175, v171, v171 row_ror:8 row_mask:0xf bank_mask:0xf
	v_max_u32_dpp v176, v171, v171 row_ror:8 row_mask:0xf bank_mask:0xf
	v_cndmask_b32_e64 v170, v173, v172, s[62:63]
	v_cndmask_b32_e64 v171, v176, v175, s[62:63]
	s_xnor_b64 s[62:63], s[54:55], s[58:59]
	s_nop 1
	v_mov_b32_dpp v174, v170 row_half_mirror row_mask:0xf bank_mask:0xf
	v_mov_b32_dpp v177, v171 row_half_mirror row_mask:0xf bank_mask:0xf
	s_nop 0
	v_min_u32_dpp v172, v174, v170 quad_perm:[3,2,1,0] row_mask:0xf bank_mask:0xf
	v_max_u32_dpp v173, v174, v170 quad_perm:[3,2,1,0] row_mask:0xf bank_mask:0xf
	v_min_u32_dpp v175, v177, v171 quad_perm:[3,2,1,0] row_mask:0xf bank_mask:0xf
	v_max_u32_dpp v176, v177, v171 quad_perm:[3,2,1,0] row_mask:0xf bank_mask:0xf
	v_cndmask_b32_e64 v170, v173, v172, s[62:63]
	v_cndmask_b32_e64 v171, v176, v175, s[62:63]
	s_xnor_b64 s[62:63], s[52:53], s[58:59]
	s_nop 1
	v_min_u32_dpp v172, v170, v170 quad_perm:[2,3,0,1] row_mask:0xf bank_mask:0xf
	v_max_u32_dpp v173, v170, v170 quad_perm:[2,3,0,1] row_mask:0xf bank_mask:0xf
	v_min_u32_dpp v175, v171, v171 quad_perm:[2,3,0,1] row_mask:0xf bank_mask:0xf
	v_max_u32_dpp v176, v171, v171 quad_perm:[2,3,0,1] row_mask:0xf bank_mask:0xf
	v_cndmask_b32_e64 v170, v173, v172, s[62:63]
	v_cndmask_b32_e64 v171, v176, v175, s[62:63]
	s_xnor_b64 s[62:63], s[50:51], s[58:59]
	s_nop 1
	v_min_u32_dpp v172, v170, v170 quad_perm:[1,0,3,2] row_mask:0xf bank_mask:0xf
	v_max_u32_dpp v173, v170, v170 quad_perm:[1,0,3,2] row_mask:0xf bank_mask:0xf
	v_min_u32_dpp v175, v171, v171 quad_perm:[1,0,3,2] row_mask:0xf bank_mask:0xf
	v_max_u32_dpp v176, v171, v171 quad_perm:[1,0,3,2] row_mask:0xf bank_mask:0xf
	v_cndmask_b32_e64 v170, v173, v172, s[62:63]
	v_cndmask_b32_e64 v171, v176, v175, s[62:63]
	s_xnor_b64 s[62:63], s[58:59], s[60:61]
	ds_bpermute_b32 v174, v146, v170
	ds_bpermute_b32 v177, v146, v171
	s_waitcnt lgkmcnt(1)
; __global__ void __launch_bounds__(NT, 2) mk_fwd(Args args) {
;     ...
;             const int e0 = EIDX[(size_t)tok * 128 + lane], e1 = EIDX[(size_t)tok * 128 + 64 + lane];
;             const float g0 = GATE[(size_t)tok * 128 + lane], g1 = GATE[(size_t)tok * 128 + 64 + lane];
	v_min_u32_e32 v172, v174, v170
	v_max_u32_e32 v173, v174, v170
	s_waitcnt lgkmcnt(0)
	v_min_u32_e32 v175, v177, v171
	v_max_u32_e32 v176, v177, v171
	v_cndmask_b32_e64 v170, v173, v172, s[62:63]
	v_cndmask_b32_e64 v171, v176, v175, s[62:63]
	s_xnor_b64 s[62:63], s[56:57], s[60:61]
	s_nop 1
	v_min_u32_dpp v172, v170, v170 row_ror:8 row_mask:0xf bank_mask:0xf
	v_max_u32_dpp v173, v170, v170 row_ror:8 row_mask:0xf bank_mask:0xf
	v_min_u32_dpp v175, v171, v171 row_ror:8 row_mask:0xf bank_mask:0xf
	v_max_u32_dpp v176, v171, v171 row_ror:8 row_mask:0xf bank_mask:0xf
	v_cndmask_b32_e64 v170, v173, v172, s[62:63]
	v_cndmask_b32_e64 v171, v176, v175, s[62:63]
	s_xnor_b64 s[62:63], s[54:55], s[60:61]
	s_nop 1
	v_mov_b32_dpp v174, v170 row_half_mirror row_mask:0xf bank_mask:0xf
	v_mov_b32_dpp v177, v171 row_half_mirror row_mask:0xf bank_mask:0xf
	s_nop 0
	v_min_u32_dpp v172, v174, v170 quad_perm:[3,2,1,0] row_mask:0xf bank_mask:0xf
	v_max_u32_dpp v173, v174, v170 quad_perm:[3,2,1,0] row_mask:0xf bank_mask:0xf
	v_min_u32_dpp v175, v177, v171 quad_perm:[3,2,1,0] row_mask:0xf bank_mask:0xf
	v_max_u32_dpp v176, v177, v171 quad_perm:[3,2,1,0] row_mask:0xf bank_mask:0xf
	v_cndmask_b32_e64 v170, v173, v172, s[62:63]
	v_cndmask_b32_e64 v171, v176, v175, s[62:63]
	s_xnor_b64 s[62:63], s[52:53], s[60:61]
	s_nop 1
	v_min_u32_dpp v172, v170, v170 quad_perm:[2,3,0,1] row_mask:0xf bank_mask:0xf
	v_max_u32_dpp v173, v170, v170 quad_perm:[2,3,0,1] row_mask:0xf bank_mask:0xf
	v_min_u32_dpp v175, v171, v171 quad_perm:[2,3,0,1] row_mask:0xf bank_mask:0xf
	v_max_u32_dpp v176, v171, v171 quad_perm:[2,3,0,1] row_mask:0xf bank_mask:0xf
	v_cndmask_b32_e64 v170, v173, v172, s[62:63]
	v_cndmask_b32_e64 v171, v176, v175, s[62:63]
	s_xnor_b64 s[62:63], s[50:51], s[60:61]
	s_nop 1
	v_min_u32_dpp v172, v170, v170 quad_perm:[1,0,3,2] row_mask:0xf bank_mask:0xf
	v_max_u32_dpp v173, v170, v170 quad_perm:[1,0,3,2] row_mask:0xf bank_mask:0xf
	v_min_u32_dpp v175, v171, v171 quad_perm:[1,0,3,2] row_mask:0xf bank_mask:0xf
	v_max_u32_dpp v176, v171, v171 quad_perm:[1,0,3,2] row_mask:0xf bank_mask:0xf
	v_cndmask_b32_e64 v170, v173, v172, s[62:63]
	v_cndmask_b32_e64 v171, v176, v175, s[62:63]
	ds_bpermute_b32 v174, v129, v170
	ds_bpermute_b32 v177, v129, v171
	s_waitcnt lgkmcnt(1)
	v_min_u32_e32 v172, v174, v170
	v_max_u32_e32 v173, v174, v170
	s_waitcnt lgkmcnt(0)
	v_min_u32_e32 v175, v177, v171
	v_max_u32_e32 v176, v177, v171
	v_cndmask_b32_e64 v170, v173, v172, s[60:61]
	v_cndmask_b32_e64 v171, v175, v176, s[60:61]
	ds_bpermute_b32 v174, v146, v170
	ds_bpermute_b32 v177, v146, v171
	s_waitcnt lgkmcnt(1)
	v_min_u32_e32 v172, v174, v170
	v_max_u32_e32 v173, v174, v170
	s_waitcnt lgkmcnt(0)
	v_min_u32_e32 v175, v177, v171
	v_max_u32_e32 v176, v177, v171
	v_cndmask_b32_e64 v170, v173, v172, s[58:59]
	v_cndmask_b32_e64 v171, v175, v176, s[58:59]
	s_nop 1
	v_min_u32_dpp v172, v170, v170 row_ror:8 row_mask:0xf bank_mask:0xf
	v_max_u32_dpp v173, v170, v170 row_ror:8 row_mask:0xf bank_mask:0xf
	v_min_u32_dpp v175, v171, v171 row_ror:8 row_mask:0xf bank_mask:0xf
	v_max_u32_dpp v176, v171, v171 row_ror:8 row_mask:0xf bank_mask:0xf
	v_cndmask_b32_e64 v170, v173, v172, s[56:57]
	v_cndmask_b32_e64 v171, v175, v176, s[56:57]
	s_nop 1
	v_mov_b32_dpp v174, v170 row_half_mirror row_mask:0xf bank_mask:0xf
	v_mov_b32_dpp v177, v171 row_half_mirror row_mask:0xf bank_mask:0xf
	s_nop 0
	v_min_u32_dpp v172, v174, v170 quad_perm:[3,2,1,0] row_mask:0xf bank_mask:0xf
	v_max_u32_dpp v173, v174, v170 quad_perm:[3,2,1,0] row_mask:0xf bank_mask:0xf
	v_min_u32_dpp v175, v177, v171 quad_perm:[3,2,1,0] row_mask:0xf bank_mask:0xf
	v_max_u32_dpp v176, v177, v171 quad_perm:[3,2,1,0] row_mask:0xf bank_mask:0xf
	v_cndmask_b32_e64 v170, v173, v172, s[54:55]
	v_cndmask_b32_e64 v171, v175, v176, s[54:55]
	s_nop 1
	v_min_u32_dpp v172, v170, v170 quad_perm:[2,3,0,1] row_mask:0xf bank_mask:0xf
	v_max_u32_dpp v173, v170, v170 quad_perm:[2,3,0,1] row_mask:0xf bank_mask:0xf
	v_min_u32_dpp v175, v171, v171 quad_perm:[2,3,0,1] row_mask:0xf bank_mask:0xf
	v_max_u32_dpp v176, v171, v171 quad_perm:[2,3,0,1] row_mask:0xf bank_mask:0xf
	v_cndmask_b32_e64 v170, v173, v172, s[52:53]
	v_cndmask_b32_e64 v171, v175, v176, s[52:53]
	s_nop 1
	v_min_u32_dpp v172, v170, v170 quad_perm:[1,0,3,2] row_mask:0xf bank_mask:0xf
	v_max_u32_dpp v173, v170, v170 quad_perm:[1,0,3,2] row_mask:0xf bank_mask:0xf
	v_min_u32_dpp v175, v171, v171 quad_perm:[1,0,3,2] row_mask:0xf bank_mask:0xf
	v_max_u32_dpp v176, v171, v171 quad_perm:[1,0,3,2] row_mask:0xf bank_mask:0xf
	v_cndmask_b32_e64 v170, v173, v172, s[50:51]
	v_cndmask_b32_e64 v171, v175, v176, s[50:51]
	v_min_u32_e32 v172, v170, v171
	v_max_u32_e32 v171, v170, v171
	v_mov_b32_e32 v170, v172
	ds_bpermute_b32 v174, v129, v170
	ds_bpermute_b32 v177, v129, v171
	s_waitcnt lgkmcnt(1)
	v_min_u32_e32 v172, v174, v170
	v_max_u32_e32 v173, v174, v170
	s_waitcnt lgkmcnt(0)
	v_min_u32_e32 v175, v177, v171
	v_max_u32_e32 v176, v177, v171
	v_cndmask_b32_e64 v170, v173, v172, s[60:61]
	v_cndmask_b32_e64 v171, v176, v175, s[60:61]
	ds_bpermute_b32 v174, v146, v170
	ds_bpermute_b32 v177, v146, v171
	s_waitcnt lgkmcnt(1)
	v_min_u32_e32 v172, v174, v170
	v_max_u32_e32 v173, v174, v170
	s_waitcnt lgkmcnt(0)
; __device__ __forceinline__ float bf_lo(unsigned u) { return __uint_as_float(u << 16); }
; __device__ __forceinline__ float bf_hi(unsigned u) { return __uint_as_float(u & 0xffff0000u); }
; #define PU_LOAD(BUF, EV, S0) do { _Pragma("unroll") for (int i = 0; i < 8; ++i) { const int row_ = __builtin_amdgcn_readlane(EV, (S0) + i); BUF[i & 3][i >> 2] = *(const u32x4*)(PU8 + (size_t)row_ * 1024 + lane * 16); } } while (0)
; __global__ void __launch_bounds__(NT, 2) mk_fwd(Args args) {
;     ...
;             for (int j = 0; j < 4; ++j) { const u32x4 a = *(const u32x4*)(HB + (size_t)tok * DM + lane * 32 + j * 8);
; #pragma unroll
;                 for (int q = 0; q < 4; ++q) hf2[j * 4 + q] = (f32x2){bf_lo(a[q]), bf_hi(a[q])}; }
;             const int e0 = EIDX[(size_t)tok * 128 + lane], e1 = EIDX[(size_t)tok * 128 + 64 + lane];
;             const float g0 = GATE[(size_t)tok * 128 + lane], g1 = GATE[(size_t)tok * 128 + 64 + lane];
;             const bool hi32 = (lane & 32) != 0, hi16 = (lane & 16) != 0; const int l3 = (lane & 3) << 4;
;     ...
;             float act0 = 0.f, act1 = 0.f;
;             u32x4 bA[4][2], bB[4][2];
; #pragma unroll
;             for (int hh = 0; hh < 2; ++hh) {
;                 const int ev = hh ? e1 : e0; const float gv = hh ? g1 : g0; float dv = 0.f;
;                 PU_LOAD(bA, ev, 0);
; #pragma unroll 1
;                 for (int s = 0; s < 64; s += 16) {
;                     PU_LOAD(bB, ev, s + 8);
;                     PU_DOT4(bA, 0, s); PU_DOT4(bA, 1, s + 4);
;                     if (s + 16 < 64) PU_LOAD(bA, ev, s + 16);
;                     PU_DOT4(bB, 0, s + 8); PU_DOT4(bB, 1, s + 12);
;                 }
;                 const float d = dv * SCL[ev];
	v_min_u32_e32 v175, v177, v171
	v_max_u32_e32 v176, v177, v171
	v_cndmask_b32_e64 v170, v173, v172, s[58:59]
	v_cndmask_b32_e64 v171, v176, v175, s[58:59]
	s_nop 1
	v_min_u32_dpp v172, v170, v170 row_ror:8 row_mask:0xf bank_mask:0xf
	v_max_u32_dpp v173, v170, v170 row_ror:8 row_mask:0xf bank_mask:0xf
	v_min_u32_dpp v175, v171, v171 row_ror:8 row_mask:0xf bank_mask:0xf
	v_max_u32_dpp v176, v171, v171 row_ror:8 row_mask:0xf bank_mask:0xf
	v_cndmask_b32_e64 v170, v173, v172, s[56:57]
	v_cndmask_b32_e64 v171, v176, v175, s[56:57]
	s_nop 1
	v_mov_b32_dpp v174, v170 row_half_mirror row_mask:0xf bank_mask:0xf
	v_mov_b32_dpp v177, v171 row_half_mirror row_mask:0xf bank_mask:0xf
	s_nop 0
	v_min_u32_dpp v172, v174, v170 quad_perm:[3,2,1,0] row_mask:0xf bank_mask:0xf
	v_max_u32_dpp v173, v174, v170 quad_perm:[3,2,1,0] row_mask:0xf bank_mask:0xf
	v_min_u32_dpp v175, v177, v171 quad_perm:[3,2,1,0] row_mask:0xf bank_mask:0xf
	v_max_u32_dpp v176, v177, v171 quad_perm:[3,2,1,0] row_mask:0xf bank_mask:0xf
	v_cndmask_b32_e64 v170, v173, v172, s[54:55]
	v_cndmask_b32_e64 v171, v176, v175, s[54:55]
	s_nop 1
	v_min_u32_dpp v172, v170, v170 quad_perm:[2,3,0,1] row_mask:0xf bank_mask:0xf
	v_max_u32_dpp v173, v170, v170 quad_perm:[2,3,0,1] row_mask:0xf bank_mask:0xf
	v_min_u32_dpp v175, v171, v171 quad_perm:[2,3,0,1] row_mask:0xf bank_mask:0xf
	v_max_u32_dpp v176, v171, v171 quad_perm:[2,3,0,1] row_mask:0xf bank_mask:0xf
	v_cndmask_b32_e64 v170, v173, v172, s[52:53]
	v_cndmask_b32_e64 v171, v176, v175, s[52:53]
	s_nop 1
	v_min_u32_dpp v172, v170, v170 quad_perm:[1,0,3,2] row_mask:0xf bank_mask:0xf
	v_max_u32_dpp v173, v170, v170 quad_perm:[1,0,3,2] row_mask:0xf bank_mask:0xf
	v_min_u32_dpp v175, v171, v171 quad_perm:[1,0,3,2] row_mask:0xf bank_mask:0xf
	v_max_u32_dpp v176, v171, v171 quad_perm:[1,0,3,2] row_mask:0xf bank_mask:0xf
	v_cndmask_b32_e64 v170, v173, v172, s[50:51]
	v_cndmask_b32_e64 v171, v176, v175, s[50:51]
	v_and_b32_e32 v172, 63, v170
	v_lshlrev_b32_e32 v172, 2, v172
	ds_bpermute_b32 v173, v172, v110
	ds_bpermute_b32 v174, v172, v156
	v_and_b32_e32 v175, 63, v171
	v_lshlrev_b32_e32 v175, 2, v175
	ds_bpermute_b32 v176, v175, v110
	ds_bpermute_b32 v177, v175, v156
	v_and_b32_e32 v172, 64, v170
	v_cmp_eq_u32_e32 vcc, 0, v172
	s_waitcnt lgkmcnt(2)
	v_lshrrev_b32_e32 v108, 7, v170
	v_cndmask_b32_e32 v178, v174, v173, vcc
	v_and_b32_e32 v175, 64, v171
	v_cmp_eq_u32_e32 vcc, 0, v175
	s_waitcnt lgkmcnt(0)
	v_lshrrev_b32_e32 v106, 7, v171
	v_cndmask_b32_e32 v179, v177, v176, vcc
	v_mov_b32_e32 v110, v178
	v_mov_b32_e32 v156, v179
	v_ashrrev_i32_e32 v181, 31, v108
	v_mov_b32_e32 v180, v108
	v_ashrrev_i32_e32 v183, 31, v106
	v_mov_b32_e32 v182, v106
	v_lshl_add_u64 v[180:181], v[180:181], 2, s[6:7]
	v_lshl_add_u64 v[182:183], v[182:183], 2, s[6:7]
	global_load_dword v218, v[180:181], off
	global_load_dword v219, v[182:183], off
	s_mov_b32 s10, 0
	v_mov_b32_e32 v107, 0
	s_waitcnt vmcnt(6)
	v_lshlrev_b32_e32 v88, 16, v32
	v_readlane_b32 s4, v108, 0
	v_readlane_b32 s30, v108, 1
	v_readlane_b32 s34, v108, 2
	v_readlane_b32 s36, v108, 3
	v_readlane_b32 s38, v108, 4
	v_readlane_b32 s40, v108, 5
	v_readlane_b32 s42, v108, 6
	v_readlane_b32 s44, v108, 7
	s_ashr_i32 s5, s4, 31
	s_ashr_i32 s31, s30, 31
	s_ashr_i32 s35, s34, 31
	s_ashr_i32 s37, s36, 31
	s_ashr_i32 s39, s38, 31
	s_ashr_i32 s41, s40, 31
	s_ashr_i32 s43, s42, 31
	s_ashr_i32 s45, s44, 31
	s_lshl_b64 s[4:5], s[4:5], 10
	s_lshl_b64 s[30:31], s[30:31], 10
	s_lshl_b64 s[34:35], s[34:35], 10
	s_lshl_b64 s[36:37], s[36:37], 10
	s_lshl_b64 s[38:39], s[38:39], 10
	s_lshl_b64 s[40:41], s[40:41], 10
	s_lshl_b64 s[42:43], s[42:43], 10
	s_lshl_b64 s[44:45], s[44:45], 10
	v_lshl_add_u64 v[48:49], v[98:99], 0, s[4:5]
	v_lshl_add_u64 v[50:51], v[98:99], 0, s[30:31]
	v_lshl_add_u64 v[52:53], v[98:99], 0, s[34:35]
	v_lshl_add_u64 v[54:55], v[98:99], 0, s[36:37]
	v_lshl_add_u64 v[56:57], v[98:99], 0, s[38:39]
	v_lshl_add_u64 v[58:59], v[98:99], 0, s[40:41]
	v_lshl_add_u64 v[60:61], v[98:99], 0, s[42:43]
	v_lshl_add_u64 v[62:63], v[98:99], 0, s[44:45]
	global_load_dwordx4 v[0:3], v[48:49], off
	global_load_dwordx4 v[4:7], v[50:51], off
	global_load_dwordx4 v[8:11], v[52:53], off
	global_load_dwordx4 v[12:15], v[54:55], off
	global_load_dwordx4 v[16:19], v[56:57], off
	global_load_dwordx4 v[20:23], v[58:59], off
	global_load_dwordx4 v[24:27], v[60:61], off
	global_load_dwordx4 v[28:31], v[62:63], off
	s_waitcnt vmcnt(11)
	v_lshlrev_b32_e32 v64, 16, v44
	v_and_b32_e32 v65, 0xffff0000, v44
	v_lshlrev_b32_e32 v66, 16, v45
	v_and_b32_e32 v67, 0xffff0000, v45
	v_lshlrev_b32_e32 v68, 16, v46
	v_and_b32_e32 v69, 0xffff0000, v46
	v_lshlrev_b32_e32 v70, 16, v47
	v_and_b32_e32 v71, 0xffff0000, v47
	v_lshlrev_b32_e32 v72, 16, v40
	v_and_b32_e32 v73, 0xffff0000, v40
	v_lshlrev_b32_e32 v74, 16, v41
	v_and_b32_e32 v75, 0xffff0000, v41
	v_lshlrev_b32_e32 v76, 16, v42
	v_and_b32_e32 v77, 0xffff0000, v42
	v_lshlrev_b32_e32 v78, 16, v43
	v_and_b32_e32 v79, 0xffff0000, v43
	v_lshlrev_b32_e32 v80, 16, v36
	v_and_b32_e32 v81, 0xffff0000, v36
	v_lshlrev_b32_e32 v82, 16, v37
	v_and_b32_e32 v83, 0xffff0000, v37
	v_lshlrev_b32_e32 v84, 16, v38
	v_and_b32_e32 v85, 0xffff0000, v38
	v_lshlrev_b32_e32 v86, 16, v39
	v_and_b32_e32 v87, 0xffff0000, v39
	v_and_b32_e32 v89, 0xffff0000, v32
	v_lshlrev_b32_e32 v90, 16, v33
	v_and_b32_e32 v91, 0xffff0000, v33
	v_lshlrev_b32_e32 v92, 16, v34
	v_and_b32_e32 v93, 0xffff0000, v34
	v_lshlrev_b32_e32 v94, 16, v35
	v_and_b32_e32 v95, 0xffff0000, v35
